# grid barrier: wave 0 issues the L1 invalidate before the first workgroup barrier (overlaps that wait as well as the arrival atomic)
# speedup vs baseline: 1.0089x; 1.0002x over previous
.LBB0_114:
	s_or_b64 exec, exec, s[0:1]
	s_cmp_lt_i32 s23, 2
	s_cbranch_scc1 .LBB0_182
	s_cmp_lt_u32 s23, 11
	s_mov_b64 s[0:1], -1
	s_cbranch_scc0 .LBB0_169
	s_waitcnt vmcnt(0)
	v_readfirstlane_b32 s2, v209
	s_nop 0
	s_cmp_lg_u32 s2, 0
	s_cbranch_scc1 .Lgbpre1
	buffer_inv sc1
.Lgbpre1:
	s_barrier
	s_mov_b64 s[0:1], exec
	v_readlane_b32 s2, v247, 11
	v_readlane_b32 s3, v247, 12
	s_and_b64 s[2:3], s[0:1], s[2:3]
	s_mov_b64 exec, s[2:3]
	s_cbranch_execz .LBB0_168
	s_add_i32 s2, 0, 0x20000
	v_mov_b32_e32 v1, s2
	s_waitcnt vmcnt(0) expcnt(0) lgkmcnt(0)
	ds_read_b32 v3, v1
	s_add_i32 s2, 0, 0x20004
	v_mov_b32_e32 v1, s2
	ds_read_b32 v1, v1
	s_waitcnt lgkmcnt(1)
	v_cmp_ne_u32_e32 vcc, 0, v3
	s_cbranch_vccnz .LBB0_132
	v_readlane_b32 s2, v247, 8
	s_mul_i32 s33, s83, s2
	s_add_u32 s2, s20, 0x1a02aa00
	s_addc_u32 s3, s21, 0
	s_add_u32 s4, s20, 0x1a02ac00
	s_addc_u32 s5, s21, 0
	s_add_u32 s6, s20, 0x1a02ad00
	s_addc_u32 s7, s21, 0
	s_add_u32 s8, s20, 0x1a02ae00
	s_addc_u32 s9, s21, 0
	s_add_u32 s10, s20, 0x1a02af00
	s_addc_u32 s11, s21, 0
	s_add_u32 s12, s20, 0x1a02b000
	s_addc_u32 s13, s21, 0
	s_add_u32 s14, s20, 0x1a02b100
	s_addc_u32 s15, s21, 0
	s_add_u32 s24, s20, 0x1a02b200
	s_addc_u32 s25, s21, 0
	s_add_u32 s26, s20, 0x1a02b300
	s_addc_u32 s27, s21, 0
	s_add_u32 s28, s20, 0x1a02b400
	s_addc_u32 s29, s21, 0
	s_add_u32 s30, s20, 0x1a02b500
	s_addc_u32 s31, s21, 0
	s_add_u32 s34, s20, 0x1a02b600
	s_addc_u32 s35, s21, 0
	s_add_u32 s52, s20, 0x1a02b700
	s_addc_u32 s53, s21, 0
	s_add_u32 s54, s20, 0x1a02b800
	s_addc_u32 s55, s21, 0
	s_add_u32 s56, s20, 0x1a02b900
	s_addc_u32 s57, s21, 0
	s_add_u32 s58, s20, 0x1a02ba00
	s_addc_u32 s59, s21, 0
	s_add_u32 s60, s20, 0x1a02bb00
	s_mul_i32 s33, s33, s82
	s_addc_u32 s61, s21, 0
	s_mov_b32 s68, 1
	v_mov_b32_e32 v17, 0
	s_branch .LBB0_120

.LBB0_299:
	s_cmp_lt_i32 s23, 3
	s_cbranch_scc1 .LBB0_367
	s_cmp_lt_u32 s23, 11
	s_mov_b64 s[0:1], -1
	s_cbranch_scc0 .LBB0_354
	s_waitcnt vmcnt(0)
	s_waitcnt vmcnt(0) lgkmcnt(0)
	v_readfirstlane_b32 s2, v209
	s_nop 0
	s_cmp_lg_u32 s2, 0
	s_cbranch_scc1 .Lgbpre2
	buffer_inv sc1

.LBB0_647:
	s_cmp_lt_i32 s23, 4
	s_cbranch_scc1 .LBB0_717
	s_cmp_lt_u32 s23, 11
	s_mov_b64 s[0:1], -1
	s_cbranch_scc0 .LBB0_704
	s_waitcnt vmcnt(0)
	s_waitcnt vmcnt(0) lgkmcnt(0)
	v_readfirstlane_b32 s2, v209
	s_nop 0
	s_cmp_lg_u32 s2, 0
	s_cbranch_scc1 .Lgbpre3
	buffer_inv sc1
.Lgbpre3:
	s_barrier
	s_mov_b64 s[0:1], exec
	v_readlane_b32 s2, v247, 11
	v_readlane_b32 s3, v247, 12
	s_and_b64 s[2:3], s[0:1], s[2:3]
	s_mov_b64 exec, s[2:3]
	s_cbranch_execz .LBB0_703
	s_add_i32 s2, 0, 0x20000
	v_mov_b32_e32 v1, s2
	s_waitcnt vmcnt(0) expcnt(0) lgkmcnt(0)
	ds_read_b32 v3, v1
	s_add_i32 s2, 0, 0x20004
	v_mov_b32_e32 v1, s2
	ds_read_b32 v1, v1
	s_waitcnt lgkmcnt(1)
	v_cmp_ne_u32_e32 vcc, 0, v3
	s_cbranch_vccnz .LBB0_667
	v_readlane_b32 s2, v247, 8
	s_mul_i32 s33, s83, s2
	s_add_u32 s2, s20, 0x1a02aa00
	s_addc_u32 s3, s21, 0
	s_add_u32 s4, s20, 0x1a02ac00
	s_addc_u32 s5, s21, 0
	s_add_u32 s6, s20, 0x1a02ad00
	s_addc_u32 s7, s21, 0
	s_add_u32 s8, s20, 0x1a02ae00
	s_addc_u32 s9, s21, 0
	s_add_u32 s10, s20, 0x1a02af00
	s_addc_u32 s11, s21, 0
	s_add_u32 s12, s20, 0x1a02b000
	s_addc_u32 s13, s21, 0
	s_add_u32 s14, s20, 0x1a02b100
	s_addc_u32 s15, s21, 0
	s_add_u32 s16, s20, 0x1a02b200
	s_addc_u32 s17, s21, 0
	s_add_u32 s24, s20, 0x1a02b300
	s_addc_u32 s25, s21, 0
	s_add_u32 s26, s20, 0x1a02b400
	s_addc_u32 s27, s21, 0
	s_add_u32 s28, s20, 0x1a02b500
	s_addc_u32 s29, s21, 0
	s_add_u32 s30, s20, 0x1a02b600
	s_addc_u32 s31, s21, 0
	s_add_u32 s34, s20, 0x1a02b700
	s_addc_u32 s35, s21, 0
	s_add_u32 s44, s20, 0x1a02b800
	s_addc_u32 s45, s21, 0
	s_add_u32 s46, s20, 0x1a02b900
	s_addc_u32 s47, s21, 0
	s_add_u32 s48, s20, 0x1a02ba00
	s_addc_u32 s49, s21, 0
	s_add_u32 s50, s20, 0x1a02bb00
	s_mul_i32 s33, s33, s82
	s_addc_u32 s51, s21, 0
	s_mov_b32 s58, 1
	v_mov_b32_e32 v17, 0
	s_branch .LBB0_653

.LBB0_882:
	s_setprio 0
	s_cmp_lt_i32 s23, 5
	s_cbranch_scc1 .LBB0_952
	s_cmp_lt_u32 s23, 11
	s_mov_b64 s[0:1], -1
	s_cbranch_scc0 .LBB0_939
	s_waitcnt vmcnt(0)
	s_waitcnt vmcnt(0) lgkmcnt(0)
	v_readfirstlane_b32 s2, v209
	s_nop 0
	s_cmp_lg_u32 s2, 0
	s_cbranch_scc1 .Lgbpre4
	buffer_inv sc1

.LBB0_972:
	s_cmp_lt_i32 s23, 6
	s_cbranch_scc1 .LBB0_1040
	s_cmp_lt_u32 s23, 11
	s_mov_b64 s[0:1], -1
	s_cbranch_scc0 .LBB0_1027
	s_waitcnt vmcnt(0)
	s_waitcnt vmcnt(0) lgkmcnt(0)
	v_readfirstlane_b32 s2, v209
	s_nop 0
	s_cmp_lg_u32 s2, 0
	s_cbranch_scc1 .Lgbpre5
	buffer_inv sc1
.Lgbpre5:
	s_barrier
	s_mov_b64 s[0:1], exec
	v_readlane_b32 s2, v247, 11
	v_readlane_b32 s3, v247, 12
	s_and_b64 s[2:3], s[0:1], s[2:3]
	s_mov_b64 exec, s[2:3]
	s_cbranch_execz .LBB0_1026
	s_add_i32 s2, 0, 0x20000
	v_mov_b32_e32 v1, s2
	s_waitcnt vmcnt(0) expcnt(0) lgkmcnt(0)
	ds_read_b32 v3, v1
	s_add_i32 s2, 0, 0x20004
	v_mov_b32_e32 v1, s2
	ds_read_b32 v1, v1
	s_waitcnt lgkmcnt(1)
	v_cmp_ne_u32_e32 vcc, 0, v3
	s_cbranch_vccnz .LBB0_990
	v_readlane_b32 s2, v247, 8
	s_mul_i32 s33, s83, s2
	s_add_u32 s2, s20, 0x1a02aa00
	s_addc_u32 s3, s21, 0
	s_add_u32 s4, s20, 0x1a02ac00
	s_addc_u32 s5, s21, 0
	s_add_u32 s6, s20, 0x1a02ad00
	s_addc_u32 s7, s21, 0
	s_add_u32 s8, s20, 0x1a02ae00
	s_addc_u32 s9, s21, 0
	s_add_u32 s10, s20, 0x1a02af00
	s_addc_u32 s11, s21, 0
	s_add_u32 s12, s20, 0x1a02b000
	s_addc_u32 s13, s21, 0
	s_add_u32 s14, s20, 0x1a02b100
	s_addc_u32 s15, s21, 0
	s_add_u32 s16, s20, 0x1a02b200
	s_addc_u32 s17, s21, 0
	s_add_u32 s24, s20, 0x1a02b300
	s_addc_u32 s25, s21, 0
	s_add_u32 s26, s20, 0x1a02b400
	s_addc_u32 s27, s21, 0
	s_add_u32 s28, s20, 0x1a02b500
	s_addc_u32 s29, s21, 0
	s_add_u32 s30, s20, 0x1a02b600
	s_addc_u32 s31, s21, 0
	s_add_u32 s34, s20, 0x1a02b700
	s_addc_u32 s35, s21, 0
	s_add_u32 s38, s20, 0x1a02b800
	s_addc_u32 s39, s21, 0
	s_add_u32 s44, s20, 0x1a02b900
	s_addc_u32 s45, s21, 0
	s_add_u32 s46, s20, 0x1a02ba00
	s_addc_u32 s47, s21, 0
	s_add_u32 s48, s20, 0x1a02bb00
	s_mul_i32 s33, s33, s82
	s_addc_u32 s49, s21, 0
	s_mov_b32 s56, 1
	v_mov_b32_e32 v17, 0
	s_branch .LBB0_978

.LBB0_1057:
	s_or_b64 exec, exec, s[0:1]
	s_cmp_lt_i32 s23, 7
	s_cbranch_scc1 .LBB0_1125
	s_cmp_lt_u32 s23, 11
	s_mov_b64 s[0:1], -1
	s_cbranch_scc0 .LBB0_1112
	s_waitcnt vmcnt(0)
	s_waitcnt vmcnt(0) lgkmcnt(0)
	v_readfirstlane_b32 s2, v209
	s_nop 0
	s_cmp_lg_u32 s2, 0
	s_cbranch_scc1 .Lgbpre6
	buffer_inv sc1
.Lgbpre6:
	s_barrier
	s_mov_b64 s[0:1], exec
	v_readlane_b32 s2, v247, 11
	v_readlane_b32 s3, v247, 12
	s_and_b64 s[2:3], s[0:1], s[2:3]
	s_mov_b64 exec, s[2:3]
	s_cbranch_execz .LBB0_1111
	s_add_i32 s2, 0, 0x20000
	v_mov_b32_e32 v1, s2
	s_waitcnt vmcnt(0) expcnt(0) lgkmcnt(0)
	ds_read_b32 v3, v1
	s_add_i32 s2, 0, 0x20004
	v_mov_b32_e32 v1, s2
	ds_read_b32 v1, v1
	s_waitcnt lgkmcnt(1)
	v_cmp_ne_u32_e32 vcc, 0, v3
	s_cbranch_vccnz .LBB0_1075
	v_readlane_b32 s2, v247, 8
	s_mul_i32 s33, s83, s2
	s_add_u32 s2, s20, 0x1a02aa00
	s_addc_u32 s3, s21, 0
	s_add_u32 s4, s20, 0x1a02ac00
	s_addc_u32 s5, s21, 0
	s_add_u32 s6, s20, 0x1a02ad00
	s_addc_u32 s7, s21, 0
	s_add_u32 s8, s20, 0x1a02ae00
	s_addc_u32 s9, s21, 0
	s_add_u32 s10, s20, 0x1a02af00
	s_addc_u32 s11, s21, 0
	s_add_u32 s12, s20, 0x1a02b000
	s_addc_u32 s13, s21, 0
	s_add_u32 s14, s20, 0x1a02b100
	s_addc_u32 s15, s21, 0
	s_add_u32 s16, s20, 0x1a02b200
	s_addc_u32 s17, s21, 0
	s_add_u32 s24, s20, 0x1a02b300
	s_addc_u32 s25, s21, 0
	s_add_u32 s26, s20, 0x1a02b400
	s_addc_u32 s27, s21, 0
	s_add_u32 s28, s20, 0x1a02b500
	s_addc_u32 s29, s21, 0
	s_add_u32 s30, s20, 0x1a02b600
	s_addc_u32 s31, s21, 0
	s_add_u32 s34, s20, 0x1a02b700
	s_addc_u32 s35, s21, 0
	s_add_u32 s38, s20, 0x1a02b800
	s_addc_u32 s39, s21, 0
	s_add_u32 s40, s20, 0x1a02b900
	s_addc_u32 s41, s21, 0
	s_add_u32 s44, s20, 0x1a02ba00
	s_addc_u32 s45, s21, 0
	s_add_u32 s46, s20, 0x1a02bb00
	s_mul_i32 s33, s33, s82
	s_addc_u32 s47, s21, 0
	s_mov_b32 s54, 1
	v_mov_b32_e32 v17, 0
	s_branch .LBB0_1063

.LBB0_1153:
	s_cmp_lt_i32 s23, 8
	s_cbranch_scc1 .LBB0_1221
	s_cmp_lt_u32 s23, 11
	s_mov_b64 s[0:1], -1
	s_cbranch_scc0 .LBB0_1208
	s_waitcnt vmcnt(0)
	s_waitcnt vmcnt(0) lgkmcnt(0)
	v_readfirstlane_b32 s2, v209
	s_nop 0
	s_cmp_lg_u32 s2, 0
	s_cbranch_scc1 .Lgbpre7
	buffer_inv sc1

.LBB0_1302:
	s_setprio 0
	s_cmp_lt_i32 s23, 9
	s_cbranch_scc1 .LBB0_1370
	s_cmp_lt_u32 s23, 11
	s_mov_b64 s[0:1], -1
	s_cbranch_scc0 .LBB0_1357
	s_waitcnt vmcnt(0)
	s_waitcnt vmcnt(0) lgkmcnt(0)
	v_readfirstlane_b32 s2, v209
	s_nop 0
	s_cmp_lg_u32 s2, 0
	s_cbranch_scc1 .Lgbpre8
	buffer_inv sc1

.LBB0_1396:
	s_and_b64 vcc, exec, s[0:1]
	s_cbranch_vccz .LBB0_1450
	s_waitcnt vmcnt(0)
	s_waitcnt vmcnt(0) lgkmcnt(0)
	v_readfirstlane_b32 s2, v209
	s_nop 0
	s_cmp_lg_u32 s2, 0
	s_cbranch_scc1 .Lgbpre9
	buffer_inv sc1
